# P0 transposes: GEMV workgroups take 3 items per wave, the rest of the items go to the other workgroups (5-6 per wave)
# speedup vs baseline: 1.0054x; 1.0054x over previous
; __device__ __forceinline__ void p0_prologue(const Args& A, char* lds, int vcu, int G) {
;     ...
;     for (int it = gw; it < NITEMS; it += NGW) {
;         int r = it;
;         if (r < I0) { transpose_item<0>(A.in[I_EINW], 1024, 6672, NP0, (bf16*)(ws + WS_WT0), scr, r, lane); continue; } r -= I0;
;         if (r < I1) { transpose_item<1>(A.in[I_OINW], 1024, 7192, NP1, (bf16*)(ws + WS_WT1), scr, r, lane); continue; } r -= I1;
;         if (r < IO) { transpose_item<2>(A.in[I_EOUTW], 2048, 1024, 1024, (bf16*)(ws + WS_WO0), scr, r, lane, G == 256 ? A.in[I_ENORMG] : nullptr); continue; } r -= IO;
;         if (r < IO) { transpose_item<2>(A.in[I_OOUTW], 2048, 1024, 1024, (bf16*)(ws + WS_WO1), scr, r, lane); continue; } r -= IO;
;         transpose_item<2>(A.in[I_OGLUW], 512, 512, 512, (bf16*)(ws + WS_WG), scr, r, lane);
;     }
.LBB0_33:
	s_or_b64 exec, exec, s[52:53]
	v_add_u32_e32 v18, s44, v18
	v_lshrrev_b32_e32 v180, 11, v18
	v_subrev_u32_e32 v181, 0x1800, v18
	v_lshrrev_b32_e32 v182, 3, v181
	v_and_b32_e32 v183, 31, v182
	v_lshrrev_b32_e32 v182, 5, v182
	v_and_b32_e32 v181, 7, v181
	v_lshl_add_u32 v181, v182, 3, v181
	v_subrev_u32_e32 v182, 12, v183
	v_lshl_add_u32 v181, v182, 6, v181
	v_add_u32_e32 v181, 0x1800, v181
	v_cmp_gt_u32_e32 vcc, 12, v183
	v_mov_b32_e32 v182, 0x10000
	s_nop 1
	v_cndmask_b32_e32 v181, v181, v182, vcc
	v_cmp_eq_u32_e32 vcc, 3, v180
	v_lshrrev_b32_e32 v182, 9, v18
	v_subrev_u32_e32 v183, 0x300, v18
	v_cndmask_b32_e32 v181, v18, v181, vcc
	v_cmp_eq_u32_e32 vcc, 4, v180
	v_cmp_eq_u32_e64 s[98:99], 20, v182
	s_or_b64 vcc, vcc, s[98:99]
	s_nop 1
	v_cndmask_b32_e32 v18, v181, v183, vcc
	v_cmp_lt_i32_e32 vcc, s94, v18
	s_or_b64 s[50:51], vcc, s[50:51]
	v_lshlrev_b32_e32 v27, 5, v18
	s_andn2_b64 exec, exec, s[50:51]
	s_cbranch_execz .LBB0_287
